# MLA: stage t+2 LDS-DMA pieces spread over region Y and the exp/PV block instead of one burst behind the mid-stage barrier
# speedup vs baseline: 1.0266x; 1.0097x over previous
.LBB0_527:
	ds_read_b64_tr_b16 v[68:69], v214 offset:28672
	ds_read_b64_tr_b16 v[70:71], v214 offset:29184
	ds_read_b64_tr_b16 v[158:159], v214 offset:36864
	ds_read_b64_tr_b16 v[160:161], v214 offset:37376
	ds_read_b64_tr_b16 v[72:73], v214 offset:29696
	ds_read_b64_tr_b16 v[74:75], v214 offset:30208
	ds_read_b64_tr_b16 v[162:163], v214 offset:37888
	ds_read_b64_tr_b16 v[164:165], v214 offset:38400
	ds_read_b64_tr_b16 v[76:77], v214 offset:30720
	ds_read_b64_tr_b16 v[78:79], v214 offset:31232
	ds_read_b64_tr_b16 v[166:167], v214 offset:38912
	ds_read_b64_tr_b16 v[168:169], v214 offset:39424
	ds_read_b64_tr_b16 v[98:99], v214 offset:31744
	ds_read_b64_tr_b16 v[100:101], v214 offset:32256
	ds_read_b64_tr_b16 v[170:171], v214 offset:39936
	ds_read_b64_tr_b16 v[172:173], v214 offset:40448
	s_add_i32 s13, s13, 1
	v_exp_f32_e32 v50, v50
	v_exp_f32_e32 v51, v51
	v_exp_f32_e32 v52, v52
	v_exp_f32_e32 v53, v53
	v_exp_f32_e32 v54, v54
	v_exp_f32_e32 v55, v55
	v_exp_f32_e32 v56, v56
	v_exp_f32_e32 v57, v57
	v_pk_add_f32 v[174:175], v[50:51], v[52:53]
	v_pk_add_f32 v[174:175], v[174:175], v[54:55]
	v_pk_add_f32 v[174:175], v[174:175], v[56:57]
	v_cvt_pk_bf16_f32 v50, v50, v51
	v_cvt_pk_bf16_f32 v51, v52, v53
	v_cvt_pk_bf16_f32 v52, v54, v55
	v_cvt_pk_bf16_f32 v53, v56, v57
	v_exp_f32_e32 v58, v58
	v_exp_f32_e32 v59, v59
	s_waitcnt lgkmcnt(12)
	v_mfma_f32_32x32x16_bf16 v[2:17], v[68:71], v[50:53], v[2:17]
	v_exp_f32_e32 v60, v60
	v_exp_f32_e32 v61, v61
	v_exp_f32_e32 v62, v62
	v_mfma_f32_32x32x16_bf16 v[18:33], v[158:161], v[50:53], v[18:33]
	s_and_b64 vcc, exec, s[100:101]
	s_cbranch_vccnz .Lmla_dsk4
	s_mov_b32 m0, s40
	s_nop 0
	global_load_lds_dwordx4 v[152:153], off
.Lmla_dsk4:
	v_exp_f32_e32 v63, v63
	v_exp_f32_e32 v64, v64
	v_exp_f32_e32 v65, v65
	v_pk_add_f32 v[174:175], v[174:175], v[58:59]
	v_pk_add_f32 v[174:175], v[174:175], v[60:61]
	v_pk_add_f32 v[174:175], v[174:175], v[62:63]
	v_pk_add_f32 v[174:175], v[174:175], v[64:65]
	v_cvt_pk_bf16_f32 v54, v58, v59
	v_cvt_pk_bf16_f32 v55, v60, v61
	v_cvt_pk_bf16_f32 v56, v62, v63
	v_cvt_pk_bf16_f32 v57, v64, v65
	v_exp_f32_e32 v82, v82
	v_exp_f32_e32 v83, v83
	s_waitcnt lgkmcnt(8)
	v_mfma_f32_32x32x16_bf16 v[2:17], v[72:75], v[54:57], v[2:17]
	v_exp_f32_e32 v84, v84
	v_exp_f32_e32 v85, v85
	v_exp_f32_e32 v86, v86
	v_mfma_f32_32x32x16_bf16 v[18:33], v[162:165], v[54:57], v[18:33]
	s_and_b64 vcc, exec, s[100:101]
	s_cbranch_vccnz .Lmla_dsk5
	s_mov_b32 m0, s41
	s_nop 0
	global_load_lds_dwordx4 v[184:185], off
.Lmla_dsk5:
	v_exp_f32_e32 v87, v87
	v_exp_f32_e32 v88, v88
	v_exp_f32_e32 v89, v89
	v_pk_add_f32 v[176:177], v[82:83], v[84:85]
	v_pk_add_f32 v[176:177], v[176:177], v[86:87]
	v_pk_add_f32 v[176:177], v[176:177], v[88:89]
	v_cvt_pk_bf16_f32 v58, v82, v83
	v_cvt_pk_bf16_f32 v59, v84, v85
	v_cvt_pk_bf16_f32 v60, v86, v87
	v_cvt_pk_bf16_f32 v61, v88, v89
	v_exp_f32_e32 v90, v90
	v_exp_f32_e32 v91, v91
	s_waitcnt lgkmcnt(4)
	v_mfma_f32_32x32x16_bf16 v[2:17], v[76:79], v[58:61], v[2:17]
	v_exp_f32_e32 v92, v92
	v_exp_f32_e32 v93, v93
	v_exp_f32_e32 v94, v94
	v_mfma_f32_32x32x16_bf16 v[18:33], v[166:169], v[58:61], v[18:33]
	v_exp_f32_e32 v95, v95
	v_exp_f32_e32 v96, v96
	v_exp_f32_e32 v97, v97
	v_pk_add_f32 v[176:177], v[176:177], v[90:91]
	v_pk_add_f32 v[176:177], v[176:177], v[92:93]
	v_pk_add_f32 v[176:177], v[176:177], v[94:95]
	v_pk_add_f32 v[176:177], v[176:177], v[96:97]
	v_cvt_pk_bf16_f32 v62, v90, v91
	v_cvt_pk_bf16_f32 v63, v92, v93
	v_cvt_pk_bf16_f32 v64, v94, v95
	v_cvt_pk_bf16_f32 v65, v96, v97
	v_pk_add_f32 v[174:175], v[174:175], v[176:177]
	s_add_i32 s0, s75, 0xa000
	s_cmp_lt_i32 s75, 0x14000
	s_cselect_b32 s75, s0, 0
	s_addk_i32 s38, 0x80
	v_add_f32_e32 v176, v174, v175
	s_waitcnt lgkmcnt(0)
	v_mfma_f32_32x32x16_bf16 v[2:17], v[98:101], v[62:65], v[2:17]
	v_add_f32_e32 v231, v66, v176
	s_cmp_lg_u32 s13, 16
	v_mfma_f32_32x32x16_bf16 v[18:33], v[170:173], v[62:65], v[18:33]
	s_cbranch_scc0 .LBB0_517

.LBB0_536:
	s_waitcnt lgkmcnt(0)
	s_nop 0
	v_mfma_f32_32x32x16_bf16 v[50:65], v[182:185], v[106:109], v[34:49]
	v_exp_f32_e32 v183, v90
	v_exp_f32_e32 v182, v66
	v_exp_f32_e32 v91, v91
	v_pk_add_f32 v[184:185], v[182:183], 0 op_sel_hi:[1,0]
	v_cvt_pk_bf16_f32 v66, v183, v91
	v_mfma_f32_32x32x16_bf16 v[50:65], v[178:181], v[110:113], v[50:65]
	v_exp_f32_e32 v90, v67
	v_exp_f32_e32 v181, v92
	v_exp_f32_e32 v180, v68
	v_pk_add_f32 v[184:185], v[90:91], v[184:185]
	v_cvt_pk_bf16_f32 v178, v182, v90
	v_pk_add_f32 v[90:91], v[180:181], v[184:185]
	v_mfma_f32_32x32x16_bf16 v[50:65], v[174:177], v[114:117], v[50:65]
	v_exp_f32_e32 v93, v93
	v_exp_f32_e32 v92, v69
	v_exp_f32_e32 v175, v94
	v_cvt_pk_bf16_f32 v67, v181, v93
	v_pk_add_f32 v[68:69], v[92:93], v[90:91]
	v_cvt_pk_bf16_f32 v179, v180, v92
	v_mfma_f32_32x32x16_bf16 v[50:65], v[170:173], v[118:121], v[50:65]
	v_exp_f32_e32 v174, v70
	v_exp_f32_e32 v91, v95
	v_exp_f32_e32 v90, v71
	v_pk_add_f32 v[70:71], v[174:175], v[68:69]
	v_cvt_pk_bf16_f32 v68, v175, v91
	v_cvt_pk_bf16_f32 v180, v174, v90
	v_pk_add_f32 v[70:71], v[90:91], v[70:71]
	v_mfma_f32_32x32x16_bf16 v[50:65], v[86:89], v[122:125], v[50:65]
	v_exp_f32_e32 v87, v96
	v_exp_f32_e32 v86, v72
	v_exp_f32_e32 v89, v97
	v_pk_add_f32 v[70:71], v[86:87], v[70:71]
	v_cvt_pk_bf16_f32 v69, v87, v89
	v_mfma_f32_32x32x16_bf16 v[50:65], v[82:85], v[126:129], v[50:65]
	v_exp_f32_e32 v88, v73
	v_exp_f32_e32 v73, v98
	v_exp_f32_e32 v72, v74
	v_pk_add_f32 v[70:71], v[88:89], v[70:71]
	v_cvt_pk_bf16_f32 v181, v86, v88
	v_pk_add_f32 v[70:71], v[72:73], v[70:71]
	v_mfma_f32_32x32x16_bf16 v[82:97], v[166:169], v[106:109], v[34:49]
	v_exp_f32_e32 v99, v99
	v_exp_f32_e32 v98, v75
	v_exp_f32_e32 v167, v100
	v_pk_add_f32 v[168:169], v[98:99], v[70:71]
	v_cvt_pk_bf16_f32 v70, v73, v99
	v_cvt_pk_bf16_f32 v74, v72, v98
	v_mfma_f32_32x32x16_bf16 v[82:97], v[162:165], v[110:113], v[82:97]
	v_exp_f32_e32 v166, v76
	v_exp_f32_e32 v73, v101
	v_exp_f32_e32 v72, v77
	v_pk_add_f32 v[76:77], v[166:167], v[168:169]
	v_cvt_pk_bf16_f32 v71, v167, v73
	v_pk_add_f32 v[76:77], v[72:73], v[76:77]
	v_cvt_pk_bf16_f32 v75, v166, v72
	v_mfma_f32_32x32x16_bf16 v[82:97], v[158:161], v[114:117], v[82:97]
	v_exp_f32_e32 v99, v102
	v_exp_f32_e32 v98, v78
	v_exp_f32_e32 v101, v103
	v_pk_add_f32 v[76:77], v[98:99], v[76:77]
	v_cvt_pk_bf16_f32 v72, v99, v101
	v_mfma_f32_32x32x16_bf16 v[82:97], v[154:157], v[118:121], v[82:97]
	v_exp_f32_e32 v100, v79
	v_exp_f32_e32 v79, v104
	v_exp_f32_e32 v78, v80
	v_pk_add_f32 v[76:77], v[100:101], v[76:77]
	s_nop 0
	v_pk_add_f32 v[102:103], v[78:79], v[76:77]
	v_cvt_pk_bf16_f32 v76, v98, v100
	v_mfma_f32_32x32x16_bf16 v[82:97], v[150:153], v[122:125], v[82:97]
	v_exp_f32_e32 v99, v105
	v_exp_f32_e32 v98, v81
	v_cvt_pk_bf16_f32 v73, v79, v99
	v_pk_add_f32 v[80:81], v[98:99], v[102:103]
	v_cvt_pk_bf16_f32 v77, v78, v98
	v_add_f32_e32 v150, v80, v81
	v_mfma_f32_32x32x16_bf16 v[82:97], v[146:149], v[126:129], v[82:97]
	s_waitcnt vmcnt(0)
	s_barrier
	s_cmp_gt_u32 s13, 13
	s_cselect_b64 s[24:25], -1, 0
	s_and_b64 s[100:101], s[24:25], s[18:19]
	s_and_b64 vcc, exec, s[100:101]
	s_cbranch_vccnz .Lmla_nodma
	s_and_b64 s[24:25], s[24:25], exec
	s_movk_i32 s30, 0xf900
	s_cselect_b32 s25, s15, s9
	s_cselect_b32 s24, s14, s8
	s_cselect_b32 s0, s17, s11
	s_cselect_b32 s4, s16, s10
	s_cselect_b32 s30, s30, 0x100
	s_cmp_gt_i32 s75, 0x9fff
	s_cselect_b32 s31, s68, 0x14000
	s_add_i32 s31, s31, s75
	s_add_u32 s40, s51, s4
	s_addc_u32 s41, s71, s0
	s_add_u32 s54, s44, s24
	s_addc_u32 s55, s45, s25
	s_add_i32 s4, s30, s38
	v_lshl_add_u64 v[154:155], v[190:191], 0, s[4:5]
	v_lshl_add_u64 v[152:153], v[216:217], 0, s[24:25]
	v_lshl_add_u64 v[154:155], v[154:155], 4, s[54:55]
	s_add_i32 s24, s4, s12
	v_lshl_add_u64 v[156:157], v[186:187], 0, s[4:5]
	s_ashr_i32 s25, s24, 31
	s_add_i32 s30, s28, s31
	v_lshl_add_u64 v[182:183], v[154:155], 0, s[26:27]
	v_lshl_add_u64 v[156:157], v[156:157], 4, s[40:41]
	s_lshl_b64 s[24:25], s[24:25], 6
	s_add_i32 s54, s30, 0x400
	s_add_i32 s55, s29, s31
	s_add_i32 s55, s55, 0x4000
	v_lshl_add_u64 v[152:153], v[152:153], 0, s[24:25]
	s_add_i32 s40, s37, s31
	s_add_i32 s41, s40, 0x8000
	s_add_i32 s40, s40, 0x6000
	v_lshl_add_u64 v[184:185], v[152:153], 0, s[48:49]
	s_mov_b32 m0, s30
	s_nop 0
	global_load_lds_dwordx4 v[154:155], off
.Lmla_nodma:
	ds_read_b64_tr_b16 v[78:79], v214 offset:32768
	ds_read_b64_tr_b16 v[80:81], v214 offset:33280
	ds_read_b64_tr_b16 v[98:99], v214 offset:33792
	ds_read_b64_tr_b16 v[100:101], v214 offset:34304
	ds_read_b64_tr_b16 v[102:103], v214 offset:34816
	ds_read_b64_tr_b16 v[104:105], v214 offset:35328
	ds_read_b64_tr_b16 v[146:147], v214 offset:35840
	ds_read_b64_tr_b16 v[148:149], v214 offset:36352
	v_mfma_f32_32x32x16_bf16 v[2:17], v[142:145], v[66:69], v[2:17]
	s_nop 2
	v_max_f32_e32 v142, v82, v82
	v_max_f32_e32 v143, v50, v50
	v_max_f32_e32 v142, v143, v142
	v_mfma_f32_32x32x16_bf16 v[2:17], v[138:141], v[70:73], v[2:17]
	v_max3_f32 v138, v142, v51, v83
	v_max3_f32 v138, v138, v52, v84
	v_max3_f32 v138, v138, v53, v85
	s_and_b64 vcc, exec, s[100:101]
	s_cbranch_vccnz .Lmla_dsk2
	s_mov_b32 m0, s54
	s_nop 0
	global_load_lds_dwordx4 v[182:183], off
.Lmla_dsk2:
	v_mfma_f32_32x32x16_bf16 v[2:17], v[134:137], v[178:181], v[2:17]
	v_max3_f32 v134, v138, v54, v86
	v_max3_f32 v134, v134, v55, v87
	v_max3_f32 v134, v134, v56, v88
	v_mfma_f32_32x32x16_bf16 v[2:17], v[130:133], v[74:77], v[2:17]
	v_max3_f32 v130, v134, v57, v89
	v_max3_f32 v130, v130, v58, v90
	v_max3_f32 v130, v130, v59, v91
	s_waitcnt lgkmcnt(0)
	v_mfma_f32_32x32x16_bf16 v[18:33], v[78:81], v[66:69], v[18:33]
	v_max3_f32 v66, v130, v60, v92
	v_max3_f32 v66, v66, v61, v93
	v_max3_f32 v66, v66, v62, v94
	s_and_b64 vcc, exec, s[100:101]
	s_cbranch_vccnz .Lmla_dsk3
	s_mov_b32 m0, s55
	s_nop 0
	global_load_lds_dwordx4 v[156:157], off
.Lmla_dsk3:
	v_mfma_f32_32x32x16_bf16 v[18:33], v[98:101], v[70:73], v[18:33]
	v_max3_f32 v66, v66, v63, v95
	v_max3_f32 v66, v66, v64, v96
	v_max3_f32 v67, v66, v65, v97
	v_add_f32_e32 v66, v231, v150
	v_mfma_f32_32x32x16_bf16 v[18:33], v[102:105], v[178:181], v[18:33]
	v_mov_b32_e32 v68, v67
	s_nop 1
	v_permlane32_swap_b32_e32 v67, v68
	v_max_f32_e32 v68, v68, v68
	v_max_f32_e32 v67, v67, v67
	v_max_f32_e32 v67, v67, v68
	v_mfma_f32_32x32x16_bf16 v[18:33], v[146:149], v[74:77], v[18:33]
	v_cmp_lt_f32_e32 vcc, s69, v67
	s_cbranch_vccz .LBB0_527
	v_max_f32_e32 v34, v67, v67
	v_max_f32_e32 v36, 0, v34
	v_exp_f32_e64 v38, -v36
	v_add_f32_e32 v215, v215, v36
	v_xor_b32_e32 v34, 0x80000000, v215
	v_pk_add_f32 v[50:51], v[50:51], v[36:37] op_sel_hi:[1,0] neg_lo:[0,1] neg_hi:[0,1]
	v_pk_add_f32 v[82:83], v[82:83], v[36:37] op_sel_hi:[1,0] neg_lo:[0,1] neg_hi:[0,1]
	v_pk_add_f32 v[52:53], v[52:53], v[36:37] op_sel_hi:[1,0] neg_lo:[0,1] neg_hi:[0,1]
	v_pk_add_f32 v[84:85], v[84:85], v[36:37] op_sel_hi:[1,0] neg_lo:[0,1] neg_hi:[0,1]
	v_pk_add_f32 v[54:55], v[54:55], v[36:37] op_sel_hi:[1,0] neg_lo:[0,1] neg_hi:[0,1]
	v_pk_add_f32 v[86:87], v[86:87], v[36:37] op_sel_hi:[1,0] neg_lo:[0,1] neg_hi:[0,1]
	v_pk_add_f32 v[56:57], v[56:57], v[36:37] op_sel_hi:[1,0] neg_lo:[0,1] neg_hi:[0,1]
	v_pk_add_f32 v[88:89], v[88:89], v[36:37] op_sel_hi:[1,0] neg_lo:[0,1] neg_hi:[0,1]
	v_pk_add_f32 v[58:59], v[58:59], v[36:37] op_sel_hi:[1,0] neg_lo:[0,1] neg_hi:[0,1]
	v_pk_add_f32 v[90:91], v[90:91], v[36:37] op_sel_hi:[1,0] neg_lo:[0,1] neg_hi:[0,1]
	v_pk_add_f32 v[60:61], v[60:61], v[36:37] op_sel_hi:[1,0] neg_lo:[0,1] neg_hi:[0,1]
	v_pk_add_f32 v[92:93], v[92:93], v[36:37] op_sel_hi:[1,0] neg_lo:[0,1] neg_hi:[0,1]
	v_pk_add_f32 v[62:63], v[62:63], v[36:37] op_sel_hi:[1,0] neg_lo:[0,1] neg_hi:[0,1]
	v_pk_add_f32 v[94:95], v[94:95], v[36:37] op_sel_hi:[1,0] neg_lo:[0,1] neg_hi:[0,1]
	v_pk_mul_f32 v[16:17], v[16:17], v[38:39] op_sel_hi:[1,0]
	v_pk_mul_f32 v[14:15], v[14:15], v[38:39] op_sel_hi:[1,0]
	v_pk_mul_f32 v[12:13], v[12:13], v[38:39] op_sel_hi:[1,0]
	v_pk_mul_f32 v[10:11], v[10:11], v[38:39] op_sel_hi:[1,0]
	v_pk_mul_f32 v[8:9], v[8:9], v[38:39] op_sel_hi:[1,0]
	v_pk_mul_f32 v[6:7], v[6:7], v[38:39] op_sel_hi:[1,0]
	v_pk_mul_f32 v[4:5], v[4:5], v[38:39] op_sel_hi:[1,0]
	v_pk_mul_f32 v[2:3], v[2:3], v[38:39] op_sel_hi:[1,0]
	v_pk_mul_f32 v[32:33], v[32:33], v[38:39] op_sel_hi:[1,0]
	v_pk_mul_f32 v[30:31], v[30:31], v[38:39] op_sel_hi:[1,0]
	v_pk_mul_f32 v[28:29], v[28:29], v[38:39] op_sel_hi:[1,0]
	v_pk_mul_f32 v[26:27], v[26:27], v[38:39] op_sel_hi:[1,0]
	v_pk_mul_f32 v[24:25], v[24:25], v[38:39] op_sel_hi:[1,0]
	v_pk_mul_f32 v[22:23], v[22:23], v[38:39] op_sel_hi:[1,0]
	v_pk_mul_f32 v[20:21], v[20:21], v[38:39] op_sel_hi:[1,0]
	v_pk_mul_f32 v[18:19], v[18:19], v[38:39] op_sel_hi:[1,0]
	v_pk_add_f32 v[64:65], v[64:65], v[36:37] op_sel_hi:[1,0] neg_lo:[0,1] neg_hi:[0,1]
	v_pk_add_f32 v[96:97], v[96:97], v[36:37] op_sel_hi:[1,0] neg_lo:[0,1] neg_hi:[0,1]
	v_mul_f32_e32 v66, v66, v38
	v_mov_b32_e32 v35, v34
	v_mov_b32_e32 v36, v34
	v_mov_b32_e32 v37, v34
	v_mov_b32_e32 v38, v34
	v_mov_b32_e32 v39, v34
	v_mov_b32_e32 v40, v34
	v_mov_b32_e32 v41, v34
	v_mov_b32_e32 v42, v34
	v_mov_b32_e32 v43, v34
	v_mov_b32_e32 v44, v34
	v_mov_b32_e32 v45, v34
	v_mov_b32_e32 v46, v34
	v_mov_b32_e32 v47, v34
	v_mov_b32_e32 v48, v34
	v_mov_b32_e32 v49, v34
	s_branch .LBB0_527
